# scan compute waves setprio 2 over loader waves; attention 2-deep K/V register prefetch (two register sets, vmcnt(2)); attention step-B interleave
# speedup vs baseline: 1.0083x; 1.0083x over previous
; #define SC_STORE(ck) do { float* B_ = buf + ((ck) % SC_NB) * SC_BUF; _Pragma("unroll") for (int i = 0; i < 20; ++i) { const int wi = lane + 64 * (i & 3), st = wi >> 4, q4 = wi & 15; \
;         *(f32x4*)(B_ + st * 336 + (i >> 2) * 64 + 4 * q4) = lr_[i]; } \
;         { const int st = lane >> 2, q4 = lane & 3; *(f32x4*)(B_ + st * 336 + 320 + 4 * q4) = lv; } } while (0)
; template <int DIR> __device__ __forceinline__ void rwkv_scan_dir(const Params& P, unsigned char* lds, int sb, int tid) {
;     ...
;     const int chain = sb >> 2, rq = sb & 3, b = (chain >> 2) & 3, h = chain & 3;
;     const int cbase = h * 64;
;     const size_t row0 = (size_t)b * S;
;     const int wid = tid >> 6, lane = tid & 63;
;     const bool loader = wid >= 4;
;     const int grp = wid - 4;
;     const int ltid = tid - 256;
;     f32x4 lr_[20], lv;
;     ...
;     constexpr int NCH = S / SC_CH;
;     if (loader) { SC_LOAD(grp); if (grp == 0) { SC_STORE(0); SC_LOAD(4); } }
;     __syncthreads();
;     const int rowi = (wid & 3) * 4 + (lane >> 4), j = lane & 15;
;     f32x2 sA = {0.f, 0.f}, sB = {0.f, 0.f};
.LBB0_71:
	s_or_b64 exec, exec, s[14:15]
	s_add_u32 s12, s12, 0x4c00000
	v_readlane_b32 s14, v255, 6
	s_addc_u32 s13, s13, 0
	s_lshl_b32 s22, s14, 2
	s_add_u32 s15, s12, s22
	v_readlane_b32 s14, v255, 7
	s_addc_u32 s19, s13, 0
	s_lshl_b32 s14, s14, 2
	s_add_u32 s18, s15, s14
	s_addc_u32 s19, s19, 0
	v_lshlrev_b32_e32 v128, 2, v162
	v_mov_b32_e32 v129, v153
	v_lshl_add_u64 v[130:131], s[18:19], 0, v[128:129]
	s_add_u32 s18, s26, s22
	s_addc_u32 s19, s27, 0
	v_mov_b32_e32 v125, v153
	v_lshl_add_u64 v[132:133], s[18:19], 0, v[124:125]
	s_add_u32 s18, s30, s22
	s_addc_u32 s19, s31, 0
	v_lshl_add_u64 v[134:135], s[18:19], 0, v[124:125]
	s_add_u32 s18, s24, s22
	s_addc_u32 s19, s25, 0
	s_add_u32 s10, s10, s22
	s_addc_u32 s11, s11, 0
	v_lshl_add_u64 v[138:139], s[10:11], 0, v[124:125]
	s_add_u32 s10, s28, s22
	s_addc_u32 s11, s29, 0
	v_lshl_add_u64 v[140:141], s[10:11], 0, v[124:125]
	s_add_u32 s10, s10, s14
	s_addc_u32 s11, s11, 0
	v_mov_b32_e32 v127, v153
	v_lshrrev_b32_e32 v84, 2, v217
	v_or_b32_e32 v184, v151, v164
	v_lshl_add_u64 v[142:143], s[10:11], 0, v[126:127]
	v_and_b32_e32 v84, 48, v84
	v_lshlrev_b32_e32 v85, 2, v151
	s_movk_i32 s10, 0xf80
	v_mov_b32_e32 v152, v153
	v_add_u32_e32 v181, 0x1500, v158
	v_add_u32_e32 v182, 0x2a00, v158
	v_add_u32_e32 v183, 0x3f00, v158
	v_lshl_add_u64 v[136:137], s[18:19], 0, v[124:125]
	v_lshl_or_b32 v125, v184, 2, v163
	v_or3_b32 v127, v84, v85, s10
	v_lshl_add_u32 v129, v162, 4, v206
	v_mov_b32_e32 v185, 0
	s_mov_b64 s[24:25], 0
	v_mov_b64_e32 v[144:145], v[152:153]
	v_mov_b64_e32 v[146:147], v[152:153]
	s_waitcnt lgkmcnt(0)
	s_barrier
	v_readfirstlane_b32 s10, v217
	s_cmpk_lt_u32 s10, 0x100
	s_cbranch_scc0 .Lscan0_np
	s_setprio 2
.Lscan0_np:
	s_branch .LBB0_74
.LBB0_72:
	s_or_b64 exec, exec, s[10:11]

; #define SC_YOUT(ck) do { const float* yp_ = ypart + ((ck) & 1) * SC_YP; const int st = ltid >> 4, rw = ltid & 15; \
;         const f32x4 q_ = *(const f32x4*)(yp_ + ltid * 4); const int s = (ck) * SC_CH + st; const size_t gr = row0 + (DIR ? (S - 1 - s) : s); \
;         Y[gr * 256 + cbase + rq * 16 + rw] = (q_.x + q_.y) + (q_.z + q_.w); } while (0)
; template <int DIR> __device__ __forceinline__ void rwkv_scan_dir(const Params& P, unsigned char* lds, int sb, int tid) {
;     ...
;     if (loader) SC_YOUT(NCH - 1);
;     __syncthreads();
.LBB0_86:
	s_setprio 0
	s_or_b64 exec, exec, s[24:25]
	s_and_saveexec_b64 s[10:11], s[8:9]
	s_cbranch_execz .LBB0_88
	s_waitcnt vmcnt(20)
	v_add_u32_e32 v0, 0, v159
	v_add_u32_e32 v0, 0x1c400, v0
	ds_read_b128 v[0:3], v0
	s_waitcnt vmcnt(19)
	v_add_u32_e32 v4, 0xff0, v157
	v_readlane_b32 s18, v255, 14
	v_ashrrev_i32_e32 v5, 31, v4
	v_readlane_b32 s19, v255, 15
	s_waitcnt lgkmcnt(0)
	v_mov_b32_e32 v6, v1
	v_mov_b32_e32 v7, v2
	v_lshl_add_u64 v[4:5], v[4:5], 0, s[18:19]
	v_mov_b32_e32 v1, v3
	v_lshlrev_b64 v[4:5], 10, v[4:5]
	v_pk_add_f32 v[0:1], v[6:7], v[0:1]
	s_mov_b32 s15, s23
	v_add_f32_e32 v2, v0, v1
	v_lshl_add_u64 v[0:1], s[12:13], 0, v[4:5]
	v_lshl_add_u64 v[0:1], v[0:1], 0, s[22:23]
	v_lshl_add_u64 v[0:1], v[0:1], 0, s[14:15]
	v_mov_b32_e32 v129, v153
	v_lshl_add_u64 v[0:1], v[0:1], 0, v[128:129]
	global_store_dword v[0:1], v2, off

; #define SC_STORE(ck) do { float* B_ = buf + ((ck) % SC_NB) * SC_BUF; _Pragma("unroll") for (int i = 0; i < 20; ++i) { const int wi = lane + 64 * (i & 3), st = wi >> 4, q4 = wi & 15; \
;         *(f32x4*)(B_ + st * 336 + (i >> 2) * 64 + 4 * q4) = lr_[i]; } \
;         { const int st = lane >> 2, q4 = lane & 3; *(f32x4*)(B_ + st * 336 + 320 + 4 * q4) = lv; } } while (0)
; template <int DIR> __device__ __forceinline__ void rwkv_scan_dir(const Params& P, unsigned char* lds, int sb, int tid) {
;     ...
;     const int chain = sb >> 2, rq = sb & 3, b = (chain >> 2) & 3, h = chain & 3;
;     const int cbase = h * 64;
;     const size_t row0 = (size_t)b * S;
;     const int wid = tid >> 6, lane = tid & 63;
;     const bool loader = wid >= 4;
;     const int grp = wid - 4;
;     const int ltid = tid - 256;
;     f32x4 lr_[20], lv;
;     ...
;     constexpr int NCH = S / SC_CH;
;     if (loader) { SC_LOAD(grp); if (grp == 0) { SC_STORE(0); SC_LOAD(4); } }
;     __syncthreads();
;     const int rowi = (wid & 3) * 4 + (lane >> 4), j = lane & 15;
;     f32x2 sA = {0.f, 0.f}, sB = {0.f, 0.f};
.LBB0_94:
	s_or_b64 exec, exec, s[12:13]
	s_waitcnt lgkmcnt(0)
	s_add_u32 s10, s10, 0x5c00000
	v_readlane_b32 s6, v255, 6
	s_addc_u32 s11, s11, 0
	s_lshl_b32 s22, s6, 2
	s_add_u32 s6, s10, s22
	v_readlane_b32 s12, v255, 7
	s_addc_u32 s7, s11, 0
	s_lshl_b32 s12, s12, 2
	s_add_u32 s6, s6, s12
	s_addc_u32 s7, s7, 0
	v_lshlrev_b32_e32 v128, 2, v162
	v_mov_b32_e32 v129, v153
	v_lshl_add_u64 v[130:131], s[6:7], 0, v[128:129]
	s_add_u32 s6, s26, s22
	s_addc_u32 s7, s27, 0
	v_mov_b32_e32 v125, v153
	v_lshl_add_u64 v[132:133], s[6:7], 0, v[124:125]
	s_add_u32 s6, s30, s22
	s_addc_u32 s7, s31, 0
	v_lshl_add_u64 v[134:135], s[6:7], 0, v[124:125]
	s_add_u32 s6, s24, s22
	s_addc_u32 s7, s25, 0
	v_lshl_add_u64 v[136:137], s[6:7], 0, v[124:125]
	s_add_u32 s6, s14, s22
	s_addc_u32 s7, s15, 0
	v_lshl_add_u64 v[138:139], s[6:7], 0, v[124:125]
	s_add_u32 s6, s28, s22
	s_addc_u32 s7, s29, 0
	v_lshl_add_u64 v[140:141], s[6:7], 0, v[124:125]
	s_add_u32 s6, s6, s12
	s_addc_u32 s7, s7, 0
	v_mov_b32_e32 v127, v153
	v_lshrrev_b32_e32 v84, 2, v217
	v_or_b32_e32 v164, v151, v164
	v_lshl_add_u64 v[142:143], s[6:7], 0, v[126:127]
	v_and_b32_e32 v84, 48, v84
	v_lshlrev_b32_e32 v85, 2, v151
	s_movk_i32 s6, 0xf80
	v_mov_b32_e32 v152, v153
	v_lshl_or_b32 v125, v164, 2, v163
	v_or3_b32 v127, v84, v85, s6
	v_lshl_add_u32 v129, v162, 4, v206
	v_mov_b32_e32 v162, 0
	s_mov_b64 s[14:15], 0
	v_mov_b64_e32 v[144:145], v[152:153]
	v_mov_b64_e32 v[146:147], v[152:153]
	s_barrier
	v_readfirstlane_b32 s6, v217
	s_cmpk_lt_u32 s6, 0x100
	s_cbranch_scc0 .Lscan1_np
	s_setprio 2
.Lscan1_np:
	s_branch .LBB0_97
.LBB0_95:
	s_or_b64 exec, exec, s[6:7]

; #define SC_YOUT(ck) do { const float* yp_ = ypart + ((ck) & 1) * SC_YP; const int st = ltid >> 4, rw = ltid & 15; \
;         const f32x4 q_ = *(const f32x4*)(yp_ + ltid * 4); const int s = (ck) * SC_CH + st; const size_t gr = row0 + (DIR ? (S - 1 - s) : s); \
;         Y[gr * 256 + cbase + rq * 16 + rw] = (q_.x + q_.y) + (q_.z + q_.w); } while (0)
; template <int DIR> __device__ __forceinline__ void rwkv_scan_dir(const Params& P, unsigned char* lds, int sb, int tid) {
;     ...
;     if (loader) SC_YOUT(NCH - 1);
;     __syncthreads();
.LBB0_108:
	s_setprio 0
	s_or_b64 exec, exec, s[14:15]
	s_and_saveexec_b64 s[4:5], s[8:9]
	s_cbranch_execz .LBB0_110
	s_waitcnt vmcnt(20)
	v_add_u32_e32 v0, 0, v159
	v_add_u32_e32 v0, 0x1c400, v0
	ds_read_b128 v[0:3], v0
	s_waitcnt vmcnt(19)
	v_sub_u32_e32 v4, 15, v157
	v_readlane_b32 s6, v255, 14
	v_ashrrev_i32_e32 v5, 31, v4
	v_readlane_b32 s7, v255, 15
	s_waitcnt lgkmcnt(0)
	v_mov_b32_e32 v6, v1
	v_mov_b32_e32 v7, v2
	v_lshl_add_u64 v[4:5], v[4:5], 0, s[6:7]
	v_mov_b32_e32 v1, v3
	v_lshlrev_b64 v[4:5], 10, v[4:5]
	v_pk_add_f32 v[0:1], v[6:7], v[0:1]
	s_mov_b32 s13, s23
	v_add_f32_e32 v2, v0, v1
	v_lshl_add_u64 v[0:1], s[10:11], 0, v[4:5]
	v_lshl_add_u64 v[0:1], v[0:1], 0, s[22:23]
	v_lshl_add_u64 v[0:1], v[0:1], 0, s[12:13]
	v_mov_b32_e32 v129, v153
	v_lshl_add_u64 v[0:1], v[0:1], 0, v[128:129]
	global_store_dword v[0:1], v2, off

; #define AT_LOADK(kt) do { kA = *(const u32x4*)(kp0 + (size_t)(kt) * ks0); if (tid < 256) kB = *(const u32x4*)(kp1 + (size_t)(kt) * ks1); } while (0)
; #define AT_LOADV(kt) do { vR = *(const u32x4*)(vp0 + (kt) * 64); } while (0)
; #define AT_STOREK(bi) do { bf16_t* Kw_ = (bf16_t*)(lds + (bi) * AT_KB); *(u32x4*)(Kw_ + key0 * AK + part0 * 8) = kA; if (tid < 256) *(u32x4*)(Kw_ + key1 * AK + part1 * 8) = kB; } while (0)
; #define AT_STOREV(bi) do { bf16_t* Vw_ = (bf16_t*)(lds + 2 * AT_KB + (bi) * AT_VB); *(u32x4*)(Vw_ + ve * AV + vpart * 8) = vR; } while (0)
; #define AT_QK(P0, P1, bi, CI) do { const bf16_t* Kt_ = (const bf16_t*)(lds + (bi) * AT_KB); P0 = CI; P1 = CI; \
;         _Pragma("unroll") for (int s = 0; s < 6; ++s) { const bf16x8 a0_ = *(const bf16x8*)(Kt_ + r32 * AK + 16 * s + 8 * hi), a1_ = *(const bf16x8*)(Kt_ + (32 + r32) * AK + 16 * s + 8 * hi); \
;             P0 = MFMA32(a0_, qr[s], P0); P1 = MFMA32(a1_, qr[s], P1); } } while (0)
; __device__ __forceinline__ void attn_unit(const Params& P, unsigned char* lds, int b, int h, int qb, int tid) {
;     ...
;     float mref, l_part = 0.f;
;     f32x16 o0, o1, negm, sa0, sa1, sb0, sb1;
; #pragma unroll
;     for (int i = 0; i < 16; ++i) { o0[i] = 0.f; o1[i] = 0.f; negm[i] = 0.f; }
;     AT_LOADK(0); AT_LOADV(0); AT_STOREK(0); AT_STOREV(0); AT_LOADK(1);
;     __syncthreads();
;     AT_QK(sa0, sa1, 0, negm);
;     { float mx = fmaxf(sa0[0], sa1[0]);
; #pragma unroll
;       for (int i = 1; i < 16; ++i) mx = fmaxf(mx, fmaxf(sa0[i], sa1[i]));
;       { auto rr_ = __builtin_amdgcn_permlane32_swap(__float_as_uint(mx), __float_as_uint(mx), false, false); mx = fmaxf(__uint_as_float(rr_[0]), __uint_as_float(rr_[1])); }
;       mref = mx;
; #pragma unroll
;       for (int i = 0; i < 16; ++i) { sa0[i] -= mx; sa1[i] -= mx; negm[i] = -mx; } }
;     AT_STOREK(1); AT_LOADK(2); AT_LOADV(1);
;     __syncthreads();
.LBB0_168:
	s_or_b64 exec, exec, s[10:11]
	s_mov_b64 s[10:11], 0xac00000
	v_lshl_add_u64 v[46:47], v[36:37], 0, s[10:11]
	global_load_dwordx4 v[144:147], v[46:47], off offset:128
	v_max_f32_e32 v32, v44, v44
	v_max_f32_e32 v33, v42, v42
	v_max_f32_e32 v225, v33, v32
	v_sub_f32_e32 v182, v0, v225
	v_and_b32_e32 v0, 0x3fffffc0, v49
	v_lshl_add_u32 v226, v0, 2, 0
	v_lshlrev_b32_e32 v0, 6, v222
	v_sub_u32_e32 v0, v56, v0
	v_lshl_add_u32 v229, v64, 1, v0
	v_and_b32_e32 v0, 7, v49
	v_sub_f32_e32 v183, v1, v225
	v_lshlrev_b32_e32 v0, 4, v0
	v_mov_b32_e32 v1, v153
	v_sub_f32_e32 v184, v2, v225
	v_sub_f32_e32 v185, v3, v225
	v_lshl_add_u64 v[0:1], v[52:53], 0, v[0:1]
	v_add_u32_e32 v2, v51, v54
	v_mov_b32_e32 v3, v153
	v_lshl_add_u64 v[0:1], v[2:3], 1, v[0:1]
	v_sub_f32_e32 v196, v14, v225
	v_sub_f32_e32 v197, v15, v225
	v_lshl_add_u64 v[0:1], s[12:13], 0, v[0:1]
	s_mov_b64 s[10:11], 0xac00180
	v_mov_b32_e32 v14, v153
	v_mov_b32_e32 v15, v153
	v_xor_b32_e32 v48, 0x80000000, v225
	v_sub_f32_e32 v32, v16, v225
	v_sub_f32_e32 v33, v17, v225
	v_sub_f32_e32 v34, v18, v225
	v_sub_f32_e32 v35, v19, v225
	v_sub_f32_e32 v36, v20, v225
	v_sub_f32_e32 v37, v21, v225
	v_sub_f32_e32 v38, v22, v225
	v_sub_f32_e32 v39, v23, v225
	v_sub_f32_e32 v40, v24, v225
	v_sub_f32_e32 v41, v25, v225
	v_sub_f32_e32 v42, v26, v225
	v_sub_f32_e32 v43, v27, v225
	v_sub_f32_e32 v44, v28, v225
	v_sub_f32_e32 v45, v29, v225
	v_sub_f32_e32 v46, v30, v225
	v_sub_f32_e32 v47, v31, v225
	v_sub_f32_e32 v186, v4, v225
	v_sub_f32_e32 v187, v5, v225
	v_sub_f32_e32 v188, v6, v225
	v_sub_f32_e32 v189, v7, v225
	v_sub_f32_e32 v190, v8, v225
	v_sub_f32_e32 v191, v9, v225
	v_sub_f32_e32 v192, v10, v225
	v_sub_f32_e32 v193, v11, v225
	v_sub_f32_e32 v194, v12, v225
	v_sub_f32_e32 v195, v13, v225
	v_lshl_add_u64 v[176:177], v[0:1], 0, s[10:11]
	v_mov_b32_e32 v0, v153
	v_mov_b32_e32 v1, v153
	v_mov_b32_e32 v2, v153
	v_mov_b32_e32 v4, v153
	v_mov_b32_e32 v5, v153
	v_mov_b32_e32 v6, v153
	v_mov_b32_e32 v7, v153
	v_mov_b32_e32 v8, v153
	v_mov_b32_e32 v9, v153
	v_mov_b32_e32 v10, v153
	v_mov_b32_e32 v11, v153
	v_mov_b32_e32 v12, v153
	v_mov_b32_e32 v13, v153
	v_mov_b64_e32 v[30:31], v[14:15]
	v_add_u32_e32 v228, 0, v55
	v_cndmask_b32_e64 v174, 11, 16, s[8:9]
	v_cmp_eq_u32_e64 s[8:9], 0, v223
	v_lshl_add_u32 v227, v222, 2, v226
	v_lshlrev_b32_e32 v178, 3, v50
	v_mov_b32_e32 v179, v153
	v_mul_hi_u32_u24_e32 v181, 6, v50
	v_mul_u32_u24_e32 v180, 6, v50
	v_mov_b32_e32 v230, 0
	s_mov_b64 s[92:93], 4
	v_mov_b64_e32 v[28:29], v[12:13]
	v_mov_b64_e32 v[26:27], v[10:11]
	v_mov_b64_e32 v[24:25], v[8:9]
	v_mov_b64_e32 v[22:23], v[6:7]
	v_mov_b64_e32 v[20:21], v[4:5]
	v_mov_b64_e32 v[18:19], v[2:3]
	v_mov_b64_e32 v[16:17], v[0:1]
	v_mov_b32_e32 v49, v48
	v_mov_b32_e32 v50, v48
	v_mov_b32_e32 v51, v48
	v_mov_b32_e32 v52, v48
	v_mov_b32_e32 v53, v48
	v_mov_b32_e32 v54, v48
	v_mov_b32_e32 v55, v48
	v_mov_b32_e32 v56, v48
	v_mov_b32_e32 v57, v48
	v_mov_b32_e32 v58, v48
	v_mov_b32_e32 v59, v48
	v_mov_b32_e32 v60, v48
	v_mov_b32_e32 v61, v48
	v_mov_b32_e32 v62, v48
	v_mov_b32_e32 v63, v48
	s_mov_b64 s[10:11], 3
	v_lshlrev_b64 v[204:205], v174, s[10:11]
	v_lshl_add_u64 v[204:205], v[204:205], 1, v[166:167]
	global_load_dwordx4 v[204:207], v[204:205], off
	s_and_saveexec_b64 s[10:11], s[6:7]
	v_lshl_add_u64 v[198:199], v[170:171], 0, v[180:181]
	global_load_dwordx4 v[198:201], v[198:199], off
	s_or_b64 exec, exec, s[10:11]
	global_load_dwordx4 v[208:211], v[176:177], off offset:-128
	v_readfirstlane_b32 s10, v217
	s_cmpk_lt_u32 s10, 0x100
	s_cbranch_scc1 .Latt_noprio
	s_setprio 1

.LBB0_170:
	s_add_i32 s18, s92, -4
	s_cmp_lt_u32 s18, 62
	s_cselect_b64 s[12:13], -1, 0
	s_cmp_gt_u32 s18, 61
	s_cbranch_scc1 .LBB0_174
	s_waitcnt vmcnt(2)
	ds_write_b128 v163, v[140:143]
	s_and_saveexec_b64 s[10:11], s[6:7]
	v_add_u32_e32 v64, v228, v168
	ds_write_b128 v64, v[112:115]
	s_or_b64 exec, exec, s[10:11]
.LBB0_174:
	s_cmp_lt_u32 s18, 61
	s_cselect_b64 s[28:29], -1, 0
	s_cmp_gt_u32 s18, 60
	s_waitcnt vmcnt(2)
	ds_write_b128 v165, v[144:147] offset:35840
	s_mov_b64 s[10:11], s[92:93]
	v_lshlrev_b64 v[64:65], v174, s[10:11]
	v_lshl_add_u64 v[64:65], v[64:65], 1, v[166:167]
	global_load_dwordx4 v[140:143], v[64:65], off
	s_and_saveexec_b64 s[10:11], s[6:7]
	s_cbranch_execz .LBB0_177
	v_lshl_add_u64 v[64:65], v[170:171], 0, v[178:179]
	global_load_dwordx4 v[112:115], v[64:65], off

.LBB0_178:
	v_cndmask_b32_e64 v64, 0, 1, s[12:13]
	v_cmp_ne_u32_e64 s[10:11], 1, v64
	s_andn2_b64 vcc, exec, s[12:13]
	global_load_dwordx4 v[144:147], v[176:177], off

.LBB0_184:
	s_cmp_gt_u32 s18, 59
	s_branch .LBB0_194

.LBB0_186:
	global_load_dwordx4 v[208:211], v[176:177], off offset:128

.LBB0_190:
	s_waitcnt vmcnt(2)
	ds_write_b128 v163, v[204:207] offset:13312
	s_and_saveexec_b64 s[28:29], s[6:7]
	v_add_u32_e32 v148, v228, v168
	ds_write_b128 v148, v[198:201] offset:13312
	s_or_b64 exec, exec, s[28:29]
	s_and_b64 vcc, exec, s[10:11]
	s_cbranch_vccnz .LBB0_184
.LBB0_193:
	s_waitcnt vmcnt(2)
	ds_write_b128 v165, v[208:211] offset:26624
	s_cmp_gt_u32 s18, 59
.LBB0_194:
	s_waitcnt vmcnt(2)
	s_add_u32 s28, s92, 1
	s_addc_u32 s29, s93, 0
	v_lshlrev_b64 v[204:205], v174, s[28:29]
	v_lshl_add_u64 v[204:205], v[204:205], 1, v[166:167]
	global_load_dwordx4 v[204:207], v[204:205], off
	s_and_saveexec_b64 s[28:29], s[6:7]
	s_cbranch_execz .LBB0_196
	v_lshl_add_u64 v[198:199], v[170:171], 0, v[180:181]
	v_lshl_add_u64 v[198:199], v[198:199], 0, v[172:173]
	global_load_dwordx4 v[198:201], v[198:199], off
.LBB0_196:
	s_or_b64 exec, exec, s[28:29]
	s_and_b64 vcc, exec, s[12:13]
	s_branch .LBB0_186

; __device__ __forceinline__ float halves_pair_sum(float v) { auto r = __builtin_amdgcn_permlane32_swap(__float_as_uint(v), __float_as_uint(v), false, false); return __uint_as_float(r[0]) + __uint_as_float(r[1]); }
; __device__ __forceinline__ void attn_unit(const Params& P, unsigned char* lds, int b, int h, int qb, int tid) {
;     ...
;     }
;     float l_run = halves_pair_sum(l_part);
;     if (hi == 0) wsf[32 + r32] = l_run;
.LBB0_203:
	s_waitcnt vmcnt(0)
	v_mov_b32_e32 v198, 0x3a27c5ac
	v_mov_b32_e32 v199, 1
	v_mov_b32_e32 v200, 0x3727c5ac
	v_mov_b32_e32 v201, 0x1000
	v_mov_b32_e32 v204, 0x2000
	v_mov_b32_e32 v205, 0xcb000
	v_mov_b32_e32 v206, 0xa80
	v_mov_b32_e32 v207, 0x50
	v_mov_b32_e32 v208, 0x100
	v_mov_b32_e32 v209, 0x200
	v_mov_b32_e32 v210, 0x7f800000
	v_mov_b32_e32 v211, 0x800
	s_setprio 0
	v_mov_b32_e32 v32, v230
	s_nop 1
	v_permlane32_swap_b32_e32 v230, v32
	s_and_saveexec_b64 s[6:7], s[8:9]
	s_cbranch_execz .LBB0_135
	v_add_f32_e32 v32, v230, v32
	ds_write_b32 v227, v32 offset:45184
	s_branch .LBB0_135
